# replace 4 cooperative-groups grid syncs by single-use monotonic counter barriers (release wbl2 + acquire inv kept)
# speedup vs baseline: 1.0012x; 1.0012x over previous
; __global__ void __launch_bounds__(512, 2) fwd_megakernel(Params p) {
;     ...
;     grid.sync();
.LBB0_47:
	v_lshrrev_b32_e32 v1, 20, v0
	v_lshrrev_b32_e32 v0, 10, v0
	v_or_b32_e32 v0, v0, v1
	s_movk_i32 s0, 0x3ff
	v_and_or_b32 v0, v0, s0, v200
	s_waitcnt vmcnt(0)
	s_barrier
	v_cmp_eq_u32_e64 s[0:1], 0, v0
	s_mov_b64 s[6:7], exec
	s_nop 0
	v_writelane_b32 v254, s0, 18
	s_nop 1
	v_writelane_b32 v254, s1, 19
	s_and_b64 s[0:1], s[6:7], s[0:1]
	s_mov_b64 exec, s[0:1]
	s_cbranch_execz .LBB0_57
	v_readlane_b32 s0, v254, 16
	v_readlane_b32 s1, v254, 17
	buffer_wbl2 sc1
	s_waitcnt vmcnt(0)
	s_sub_u32 s0, s0, 8
	s_subb_u32 s1, s1, 0
	s_load_dwordx2 s[0:1], s[0:1], 0x0
	v_mov_b32_e32 v2, 0
	v_mov_b32_e32 v3, 1
	s_waitcnt lgkmcnt(0)
	s_add_u32 s0, s0, 0x1e000
	s_addc_u32 s1, s1, 0
	global_atomic_add v2, v3, s[0:1]
.Lmy_gs0_poll:
	s_sleep 2
	global_load_dword v0, v2, s[0:1] sc1
	s_waitcnt vmcnt(0)
	v_readfirstlane_b32 vcc_lo, v0
	s_nop 1
	s_cmp_lt_u32 vcc_lo, 0x100
	s_cbranch_scc1 .Lmy_gs0_poll
	buffer_inv sc1
	s_waitcnt vmcnt(0)

; __global__ void __launch_bounds__(512, 2) fwd_megakernel(Params p) {
;     ...
;     grid.sync();
.LBB0_62:
	s_waitcnt vmcnt(0)
	s_barrier
	s_mov_b64 s[4:5], exec
	v_readlane_b32 s0, v254, 18
	v_readlane_b32 s1, v254, 19
	s_and_b64 s[0:1], s[4:5], s[0:1]
	s_mov_b64 exec, s[0:1]
	s_cbranch_execz .LBB0_72
	v_readlane_b32 s0, v254, 16
	v_readlane_b32 s1, v254, 17
	buffer_wbl2 sc1
	s_waitcnt vmcnt(0)
	s_sub_u32 s0, s0, 8
	s_subb_u32 s1, s1, 0
	s_load_dwordx2 s[0:1], s[0:1], 0x0
	v_mov_b32_e32 v2, 0
	v_mov_b32_e32 v3, 1
	s_waitcnt lgkmcnt(0)
	s_add_u32 s0, s0, 0x1e400
	s_addc_u32 s1, s1, 0
	global_atomic_add v2, v3, s[0:1]

; __global__ void __launch_bounds__(512, 2) fwd_megakernel(Params p) {
;     ...
;     grid.sync();
.LBB0_150:
	s_waitcnt vmcnt(0)
	s_waitcnt vmcnt(0)
	s_barrier
	s_mov_b64 s[4:5], exec
	v_readlane_b32 s0, v254, 18
	v_readlane_b32 s1, v254, 19
	s_and_b64 s[0:1], s[4:5], s[0:1]
	s_mov_b64 exec, s[0:1]
	s_cbranch_execz .LBB0_160
	v_readlane_b32 s0, v254, 16
	v_readlane_b32 s1, v254, 17
	buffer_wbl2 sc1
	s_waitcnt vmcnt(0)
	s_sub_u32 s0, s0, 8
	s_subb_u32 s1, s1, 0
	s_load_dwordx2 s[0:1], s[0:1], 0x0
	v_mov_b32_e32 v2, 0
	v_mov_b32_e32 v3, 1
	s_waitcnt lgkmcnt(0)
	s_add_u32 s0, s0, 0x1e800
	s_addc_u32 s1, s1, 0
	global_atomic_add v2, v3, s[0:1]

; __global__ void __launch_bounds__(512, 2) fwd_megakernel(Params p) {
;     ...
;     grid.sync();
.LBB0_307:
	s_waitcnt vmcnt(63) expcnt(7) lgkmcnt(15)
	s_waitcnt vmcnt(0)
	s_barrier
	s_mov_b64 s[4:5], exec
	v_readlane_b32 s0, v254, 18
	v_readlane_b32 s1, v254, 19
	s_and_b64 s[0:1], s[4:5], s[0:1]
	v_readlane_b32 s10, v254, 36
	s_mov_b64 exec, s[0:1]
	s_cbranch_execz .LBB0_317
	v_readlane_b32 s0, v254, 16
	v_readlane_b32 s1, v254, 17
	buffer_wbl2 sc1
	s_waitcnt vmcnt(0)
	s_sub_u32 s0, s0, 8
	s_subb_u32 s1, s1, 0
	s_load_dwordx2 s[0:1], s[0:1], 0x0
	v_mov_b32_e32 v2, 0
	v_mov_b32_e32 v3, 1
	s_waitcnt lgkmcnt(0)
	s_add_u32 s0, s0, 0x1ec00
	s_addc_u32 s1, s1, 0
	global_atomic_add v2, v3, s[0:1]
